# combo8 + up-GEMM epilogue un-aligned: the two wave halves keep their one-barrier stagger through the epilogue (no alignment barriers)
# baseline (speedup 1.0000x reference)
; #define PG8_LAS __attribute__((address_space(3)))
; __device__ __forceinline__ unsigned cvt_pk_bf16(float lo, float hi) { unsigned r; asm volatile("v_cvt_pk_bf16_f32 %0, %1, %2" : "=v"(r) : "v"(lo), "v"(hi)); return r; }
; #define PG8_BAR __builtin_amdgcn_s_barrier()
;     __device__ __forceinline__ void operator()(const f32x4 (&acc)[2][2][4][2], const Unit& u, int wr, int wc, int fr, int fq, PG8_LAS unsigned char* sl) const {
;         const int row0 = u.pm * BM + wr * 64 + fr, col0 = u.pn * HALF + wc * 32 + 8 * fq;
;         const PG8_LAS float* sf = (const PG8_LAS float*)sl;
;         f32x4 bw[2][2];
; #pragma unroll
;         for (int bj = 0; bj < 2; ++bj)
; #pragma unroll
;             for (int n = 0; n < 2; ++n) bw[bj][n] = *(const PG8_LAS f32x4*)(sf + 128 + bj * 32 + 8 * fq + 4 * n);
; #pragma unroll
;         for (int ai = 0; ai < 2; ++ai)
; #pragma unroll
;             for (int m = 0; m < 4; ++m) { const int row = row0 + ai * HALF + m * 16; bf16_t* rowp = O + (size_t)row * ldc + col0;
;                 const float rs = __builtin_amdgcn_rsqf(sf[ai * 64 + m * 16 + fr] * (1.0f / 2048.0f) + 1e-6f);
;                 const f32x4 a0 = acc[ai][0][m][0] * rs + bw[0][0], a1 = acc[ai][0][m][1] * rs + bw[0][1], b0 = acc[ai][1][m][0] * rs + bw[1][0], b1 = acc[ai][1][m][1] * rs + bw[1][1];
;                 const f32x2 s0 = silu_mul_pk((f32x2){a0[0], a0[1]}, (f32x2){b0[0], b0[1]}), s1 = silu_mul_pk((f32x2){a0[2], a0[3]}, (f32x2){b0[2], b0[3]});
;                 const f32x2 s2 = silu_mul_pk((f32x2){a1[0], a1[1]}, (f32x2){b1[0], b1[1]}), s3 = silu_mul_pk((f32x2){a1[2], a1[3]}, (f32x2){b1[2], b1[3]});
;                 u32x4 w; w.x = cvt_pk_bf16(s0.x, s0.y); w.y = cvt_pk_bf16(s1.x, s1.y); w.z = cvt_pk_bf16(s2.x, s2.y); w.w = cvt_pk_bf16(s3.x, s3.y);
;                 *(u32x4*)rowp = w; }
; template <class Epi, class Sched, bool ALIGN_EPI = false, bool SP2 = false>
; __device__ __forceinline__ void gemm_phase(PG8_LAS unsigned char* lds, const Gemm g, const Sched& S, const Epi& E, const int tid) {
;     ...
;         if constexpr (ALIGN_EPI) { if (wr == 0) PG8_BAR; }
;         for (int er = 0; er < Epi::REP; ++er) { E(acc, cur, wr, wc, fr, fq, lds + EPI_LDS_OFF + wid * 1024); if (Epi::REP > 1) asm volatile("" ::: "memory"); }
.LBB0_269:
	s_and_b64 vcc, exec, s[12:13]
	s_cbranch_vccz .LBB0_271
	s_nop 0
.LBB0_271:
	ds_read_b32 v128, v163
	ds_read_b128 v[144:147], v162 offset:512
	v_lshl_or_b32 v168, s74, 7, v164
	v_add_u32_e32 v166, s22, v160
	v_ashrrev_i32_e32 v169, 31, v168
	s_waitcnt lgkmcnt(0)
	v_fmamk_f32 v128, v128, 0x3a000000, v233
	v_rsq_f32_e32 v170, v128
	ds_read_b128 v[140:143], v162 offset:528
	ds_read_b128 v[132:135], v162 offset:640
	ds_read_b128 v[128:131], v162 offset:656
	s_andn2_b64 vcc, exec, s[6:7]
	s_mov_b64 s[6:7], -1
	v_pk_fma_f32 v[138:139], v[138:139], v[170:171], v[146:147] op_sel_hi:[1,0,1]
	v_pk_fma_f32 v[136:137], v[136:137], v[170:171], v[144:145] op_sel_hi:[1,0,1]
	s_waitcnt lgkmcnt(0)
	v_pk_fma_f32 v[126:127], v[126:127], v[170:171], v[142:143] op_sel_hi:[1,0,1]
	v_pk_fma_f32 v[122:123], v[122:123], v[170:171], v[134:135] op_sel_hi:[1,0,1]
	v_pk_fma_f32 v[124:125], v[124:125], v[170:171], v[140:141] op_sel_hi:[1,0,1]
	v_pk_fma_f32 v[120:121], v[120:121], v[170:171], v[132:133] op_sel_hi:[1,0,1]
	v_pk_fma_f32 v[116:117], v[116:117], v[170:171], v[128:129] op_sel_hi:[1,0,1]
	v_pk_fma_f32 v[118:119], v[118:119], v[170:171], v[130:131] op_sel_hi:[1,0,1]
	v_pk_mul_f32 v[170:171], v[136:137], s[72:73] op_sel_hi:[1,0]
	v_pk_mul_f32 v[172:173], v[138:139], s[72:73] op_sel_hi:[1,0]
	v_pk_mul_f32 v[122:123], v[138:139], v[122:123]
	v_pk_mul_f32 v[138:139], v[126:127], s[72:73] op_sel_hi:[1,0]
	v_exp_f32_e32 v170, v170
	v_exp_f32_e32 v171, v171
	v_exp_f32_e32 v172, v172
	v_exp_f32_e32 v173, v173
	v_pk_mul_f32 v[120:121], v[136:137], v[120:121]
	v_pk_mul_f32 v[136:137], v[124:125], s[72:73] op_sel_hi:[1,0]
	v_exp_f32_e32 v138, v138
	v_exp_f32_e32 v139, v139
	v_exp_f32_e32 v136, v136
	v_exp_f32_e32 v137, v137
	v_pk_add_f32 v[170:171], v[170:171], 1.0 op_sel_hi:[1,0]
	v_pk_add_f32 v[172:173], v[172:173], 1.0 op_sel_hi:[1,0]
	v_pk_add_f32 v[138:139], v[138:139], 1.0 op_sel_hi:[1,0]
	v_rcp_f32_e32 v170, v170
	v_rcp_f32_e32 v171, v171
	v_rcp_f32_e32 v172, v172
	v_rcp_f32_e32 v173, v173
	v_pk_add_f32 v[136:137], v[136:137], 1.0 op_sel_hi:[1,0]
	v_rcp_f32_e32 v138, v138
	v_rcp_f32_e32 v139, v139
	v_rcp_f32_e32 v136, v136
	v_rcp_f32_e32 v137, v137
	v_pk_mul_f32 v[118:119], v[126:127], v[118:119]
	v_pk_mul_f32 v[120:121], v[120:121], v[170:171]
	v_pk_mul_f32 v[122:123], v[122:123], v[172:173]
	v_pk_mul_f32 v[116:117], v[124:125], v[116:117]
	v_pk_mul_f32 v[118:119], v[118:119], v[138:139]
	v_pk_mul_f32 v[116:117], v[116:117], v[136:137]
	v_cvt_pk_bf16_f32 v120, v120, v121
	v_cvt_pk_bf16_f32 v121, v122, v123
	s_nop 0
	v_cvt_pk_bf16_f32 v122, v116, v117
	v_cvt_pk_bf16_f32 v123, v118, v119
	ds_read_b32 v118, v163 offset:64
	v_mov_b64_e32 v[116:117], s[92:93]
	v_mad_i64_i32 v[124:125], s[22:23], v166, s34, v[116:117]
	s_waitcnt lgkmcnt(0)
	v_fmamk_f32 v118, v118, 0x3a000000, v233
	v_rsq_f32_e32 v126, v118
	v_lshlrev_b64 v[118:119], 1, v[168:169]
	v_lshl_add_u64 v[124:125], v[124:125], 0, v[118:119]
	global_store_dwordx4 v[124:125], v[120:123], off
	v_pk_fma_f32 v[112:113], v[112:113], v[126:127], v[144:145] op_sel_hi:[1,0,1]
	v_pk_fma_f32 v[114:115], v[114:115], v[126:127], v[146:147] op_sel_hi:[1,0,1]
	v_pk_fma_f32 v[110:111], v[110:111], v[126:127], v[142:143] op_sel_hi:[1,0,1]
	v_pk_fma_f32 v[108:109], v[108:109], v[126:127], v[140:141] op_sel_hi:[1,0,1]
	v_pk_fma_f32 v[104:105], v[104:105], v[126:127], v[132:133] op_sel_hi:[1,0,1]
	v_pk_fma_f32 v[106:107], v[106:107], v[126:127], v[134:135] op_sel_hi:[1,0,1]
	v_pk_mul_f32 v[120:121], v[112:113], s[72:73] op_sel_hi:[1,0]
	v_pk_mul_f32 v[122:123], v[114:115], s[72:73] op_sel_hi:[1,0]
	v_exp_f32_e32 v120, v120
	v_exp_f32_e32 v121, v121
	v_pk_mul_f32 v[106:107], v[114:115], v[106:107]
	v_pk_mul_f32 v[104:105], v[112:113], v[104:105]
	v_pk_mul_f32 v[112:113], v[108:109], s[72:73] op_sel_hi:[1,0]
	v_pk_mul_f32 v[114:115], v[110:111], s[72:73] op_sel_hi:[1,0]
	v_exp_f32_e32 v122, v122
	v_exp_f32_e32 v123, v123
	v_exp_f32_e32 v112, v112
	v_exp_f32_e32 v113, v113
	v_exp_f32_e32 v114, v114
	v_exp_f32_e32 v115, v115
	v_pk_add_f32 v[120:121], v[120:121], 1.0 op_sel_hi:[1,0]
	v_pk_add_f32 v[122:123], v[122:123], 1.0 op_sel_hi:[1,0]
	v_rcp_f32_e32 v120, v120
	v_rcp_f32_e32 v121, v121
	v_pk_add_f32 v[112:113], v[112:113], 1.0 op_sel_hi:[1,0]
	v_pk_add_f32 v[114:115], v[114:115], 1.0 op_sel_hi:[1,0]
	v_rcp_f32_e32 v122, v122
	v_rcp_f32_e32 v123, v123
	v_rcp_f32_e32 v112, v112
	v_rcp_f32_e32 v113, v113
	v_rcp_f32_e32 v114, v114
	v_rcp_f32_e32 v115, v115
	v_pk_fma_f32 v[100:101], v[100:101], v[126:127], v[128:129] op_sel_hi:[1,0,1]
	v_pk_fma_f32 v[102:103], v[102:103], v[126:127], v[130:131] op_sel_hi:[1,0,1]
	v_pk_mul_f32 v[104:105], v[104:105], v[120:121]
	v_pk_mul_f32 v[102:103], v[110:111], v[102:103]
	v_pk_mul_f32 v[100:101], v[108:109], v[100:101]
	v_pk_mul_f32 v[106:107], v[106:107], v[122:123]
	v_pk_mul_f32 v[108:109], v[100:101], v[112:113]
	v_pk_mul_f32 v[110:111], v[102:103], v[114:115]
	v_cvt_pk_bf16_f32 v100, v104, v105
	v_cvt_pk_bf16_f32 v101, v106, v107
	v_cvt_pk_bf16_f32 v102, v108, v109
	v_or_b32_e32 v105, 16, v166
	v_cvt_pk_bf16_f32 v103, v110, v111
	ds_read_b32 v104, v163 offset:128
	v_mad_i64_i32 v[106:107], s[22:23], v105, s34, v[116:117]
	v_lshl_add_u64 v[106:107], v[106:107], 0, v[118:119]
	global_store_dwordx4 v[106:107], v[100:103], off
	s_waitcnt lgkmcnt(0)
; __device__ __forceinline__ unsigned cvt_pk_bf16(float lo, float hi) { unsigned r; asm volatile("v_cvt_pk_bf16_f32 %0, %1, %2" : "=v"(r) : "v"(lo), "v"(hi)); return r; }
;     __device__ __forceinline__ void operator()(const f32x4 (&acc)[2][2][4][2], const Unit& u, int wr, int wc, int fr, int fq, PG8_LAS unsigned char* sl) const {
;     ...
;             for (int m = 0; m < 4; ++m) { const int row = row0 + ai * HALF + m * 16; bf16_t* rowp = O + (size_t)row * ldc + col0;
;                 const float rs = __builtin_amdgcn_rsqf(sf[ai * 64 + m * 16 + fr] * (1.0f / 2048.0f) + 1e-6f);
;                 const f32x4 a0 = acc[ai][0][m][0] * rs + bw[0][0], a1 = acc[ai][0][m][1] * rs + bw[0][1], b0 = acc[ai][1][m][0] * rs + bw[1][0], b1 = acc[ai][1][m][1] * rs + bw[1][1];
;                 const f32x2 s0 = silu_mul_pk((f32x2){a0[0], a0[1]}, (f32x2){b0[0], b0[1]}), s1 = silu_mul_pk((f32x2){a0[2], a0[3]}, (f32x2){b0[2], b0[3]});
;                 const f32x2 s2 = silu_mul_pk((f32x2){a1[0], a1[1]}, (f32x2){b1[0], b1[1]}), s3 = silu_mul_pk((f32x2){a1[2], a1[3]}, (f32x2){b1[2], b1[3]});
;                 u32x4 w; w.x = cvt_pk_bf16(s0.x, s0.y); w.y = cvt_pk_bf16(s1.x, s1.y); w.z = cvt_pk_bf16(s2.x, s2.y); w.w = cvt_pk_bf16(s3.x, s3.y);
;                 *(u32x4*)rowp = w; }
	v_fmamk_f32 v104, v104, 0x3a000000, v233
	v_rsq_f32_e32 v104, v104
	s_nop 0
	v_pk_fma_f32 v[96:97], v[96:97], v[104:105], v[144:145] op_sel_hi:[1,0,1]
	v_pk_fma_f32 v[98:99], v[98:99], v[104:105], v[146:147] op_sel_hi:[1,0,1]
	v_pk_fma_f32 v[94:95], v[94:95], v[104:105], v[142:143] op_sel_hi:[1,0,1]
	v_pk_fma_f32 v[92:93], v[92:93], v[104:105], v[140:141] op_sel_hi:[1,0,1]
	v_pk_fma_f32 v[88:89], v[88:89], v[104:105], v[132:133] op_sel_hi:[1,0,1]
	v_pk_fma_f32 v[90:91], v[90:91], v[104:105], v[134:135] op_sel_hi:[1,0,1]
	v_pk_mul_f32 v[100:101], v[96:97], s[72:73] op_sel_hi:[1,0]
	v_pk_mul_f32 v[102:103], v[98:99], s[72:73] op_sel_hi:[1,0]
	v_exp_f32_e32 v100, v100
	v_exp_f32_e32 v101, v101
	v_pk_mul_f32 v[90:91], v[98:99], v[90:91]
	v_pk_mul_f32 v[88:89], v[96:97], v[88:89]
	v_pk_mul_f32 v[96:97], v[92:93], s[72:73] op_sel_hi:[1,0]
	v_pk_mul_f32 v[98:99], v[94:95], s[72:73] op_sel_hi:[1,0]
	v_exp_f32_e32 v102, v102
	v_exp_f32_e32 v103, v103
	v_exp_f32_e32 v96, v96
	v_exp_f32_e32 v97, v97
	v_exp_f32_e32 v98, v98
	v_exp_f32_e32 v99, v99
	v_pk_add_f32 v[100:101], v[100:101], 1.0 op_sel_hi:[1,0]
	v_pk_add_f32 v[102:103], v[102:103], 1.0 op_sel_hi:[1,0]
	v_rcp_f32_e32 v100, v100
	v_rcp_f32_e32 v101, v101
	v_pk_add_f32 v[96:97], v[96:97], 1.0 op_sel_hi:[1,0]
	v_pk_add_f32 v[98:99], v[98:99], 1.0 op_sel_hi:[1,0]
	v_rcp_f32_e32 v102, v102
	v_rcp_f32_e32 v103, v103
	v_rcp_f32_e32 v96, v96
	v_rcp_f32_e32 v97, v97
	v_rcp_f32_e32 v98, v98
	v_rcp_f32_e32 v99, v99
	v_pk_fma_f32 v[84:85], v[84:85], v[104:105], v[128:129] op_sel_hi:[1,0,1]
	v_pk_fma_f32 v[86:87], v[86:87], v[104:105], v[130:131] op_sel_hi:[1,0,1]
	v_pk_mul_f32 v[88:89], v[88:89], v[100:101]
	v_pk_mul_f32 v[86:87], v[94:95], v[86:87]
	v_pk_mul_f32 v[84:85], v[92:93], v[84:85]
	v_pk_mul_f32 v[90:91], v[90:91], v[102:103]
	v_pk_mul_f32 v[92:93], v[84:85], v[96:97]
	v_pk_mul_f32 v[94:95], v[86:87], v[98:99]
	v_cvt_pk_bf16_f32 v84, v88, v89
	v_cvt_pk_bf16_f32 v85, v90, v91
	v_cvt_pk_bf16_f32 v86, v92, v93
	v_or_b32_e32 v89, 32, v166
	v_cvt_pk_bf16_f32 v87, v94, v95
	ds_read_b32 v88, v163 offset:192
	v_mad_i64_i32 v[90:91], s[22:23], v89, s34, v[116:117]
	v_lshl_add_u64 v[90:91], v[90:91], 0, v[118:119]
	global_store_dwordx4 v[90:91], v[84:87], off
	s_waitcnt lgkmcnt(0)
	v_fmamk_f32 v88, v88, 0x3a000000, v233
	v_rsq_f32_e32 v88, v88
	s_nop 0
	v_pk_fma_f32 v[80:81], v[80:81], v[88:89], v[144:145] op_sel_hi:[1,0,1]
	v_pk_fma_f32 v[82:83], v[82:83], v[88:89], v[146:147] op_sel_hi:[1,0,1]
	v_pk_fma_f32 v[78:79], v[78:79], v[88:89], v[142:143] op_sel_hi:[1,0,1]
	v_pk_fma_f32 v[76:77], v[76:77], v[88:89], v[140:141] op_sel_hi:[1,0,1]
	v_pk_fma_f32 v[72:73], v[72:73], v[88:89], v[132:133] op_sel_hi:[1,0,1]
	v_pk_fma_f32 v[74:75], v[74:75], v[88:89], v[134:135] op_sel_hi:[1,0,1]
	v_pk_mul_f32 v[84:85], v[80:81], s[72:73] op_sel_hi:[1,0]
	v_pk_mul_f32 v[86:87], v[82:83], s[72:73] op_sel_hi:[1,0]
	v_exp_f32_e32 v84, v84
	v_exp_f32_e32 v85, v85
	v_pk_mul_f32 v[74:75], v[82:83], v[74:75]
	v_pk_mul_f32 v[72:73], v[80:81], v[72:73]
	v_pk_mul_f32 v[80:81], v[76:77], s[72:73] op_sel_hi:[1,0]
	v_pk_mul_f32 v[82:83], v[78:79], s[72:73] op_sel_hi:[1,0]
	v_exp_f32_e32 v86, v86
	v_exp_f32_e32 v87, v87
	v_exp_f32_e32 v80, v80
	v_exp_f32_e32 v81, v81
	v_exp_f32_e32 v82, v82
	v_exp_f32_e32 v83, v83
	v_pk_add_f32 v[84:85], v[84:85], 1.0 op_sel_hi:[1,0]
	v_pk_add_f32 v[86:87], v[86:87], 1.0 op_sel_hi:[1,0]
	v_rcp_f32_e32 v84, v84
	v_rcp_f32_e32 v85, v85
	v_pk_add_f32 v[80:81], v[80:81], 1.0 op_sel_hi:[1,0]
	v_pk_add_f32 v[82:83], v[82:83], 1.0 op_sel_hi:[1,0]
	v_rcp_f32_e32 v86, v86
	v_rcp_f32_e32 v87, v87
	v_rcp_f32_e32 v80, v80
	v_rcp_f32_e32 v81, v81
	v_rcp_f32_e32 v82, v82
	v_rcp_f32_e32 v83, v83
	v_pk_fma_f32 v[68:69], v[68:69], v[88:89], v[128:129] op_sel_hi:[1,0,1]
	v_pk_fma_f32 v[70:71], v[70:71], v[88:89], v[130:131] op_sel_hi:[1,0,1]
	v_pk_mul_f32 v[72:73], v[72:73], v[84:85]
	v_pk_mul_f32 v[70:71], v[78:79], v[70:71]
	v_pk_mul_f32 v[68:69], v[76:77], v[68:69]
	v_pk_mul_f32 v[74:75], v[74:75], v[86:87]
	v_pk_mul_f32 v[76:77], v[68:69], v[80:81]
	v_pk_mul_f32 v[78:79], v[70:71], v[82:83]
	v_cvt_pk_bf16_f32 v68, v72, v73
	v_cvt_pk_bf16_f32 v69, v74, v75
	v_cvt_pk_bf16_f32 v70, v76, v77
	v_or_b32_e32 v73, 48, v166
	v_cvt_pk_bf16_f32 v71, v78, v79
	ds_read_b32 v72, v163 offset:256
	v_mad_i64_i32 v[74:75], s[22:23], v73, s34, v[116:117]
	v_lshl_add_u64 v[74:75], v[74:75], 0, v[118:119]
	global_store_dwordx4 v[74:75], v[68:71], off
	s_waitcnt lgkmcnt(0)
	v_fmamk_f32 v72, v72, 0x3a000000, v233
	v_rsq_f32_e32 v72, v72
	s_nop 0
	v_pk_fma_f32 v[64:65], v[64:65], v[72:73], v[144:145] op_sel_hi:[1,0,1]
	v_pk_fma_f32 v[66:67], v[66:67], v[72:73], v[146:147] op_sel_hi:[1,0,1]
	v_pk_fma_f32 v[62:63], v[62:63], v[72:73], v[142:143] op_sel_hi:[1,0,1]
	v_pk_fma_f32 v[60:61], v[60:61], v[72:73], v[140:141] op_sel_hi:[1,0,1]
	v_pk_fma_f32 v[56:57], v[56:57], v[72:73], v[132:133] op_sel_hi:[1,0,1]
	v_pk_fma_f32 v[58:59], v[58:59], v[72:73], v[134:135] op_sel_hi:[1,0,1]
	v_pk_mul_f32 v[68:69], v[64:65], s[72:73] op_sel_hi:[1,0]
	v_pk_mul_f32 v[70:71], v[66:67], s[72:73] op_sel_hi:[1,0]
	v_exp_f32_e32 v68, v68
	v_exp_f32_e32 v69, v69
	v_pk_mul_f32 v[58:59], v[66:67], v[58:59]
	v_pk_mul_f32 v[56:57], v[64:65], v[56:57]
	v_pk_mul_f32 v[64:65], v[60:61], s[72:73] op_sel_hi:[1,0]
	v_pk_mul_f32 v[66:67], v[62:63], s[72:73] op_sel_hi:[1,0]
	v_exp_f32_e32 v70, v70
	v_exp_f32_e32 v71, v71
	v_exp_f32_e32 v64, v64
	v_exp_f32_e32 v65, v65
	v_exp_f32_e32 v66, v66
	v_exp_f32_e32 v67, v67
	v_pk_add_f32 v[68:69], v[68:69], 1.0 op_sel_hi:[1,0]
	v_pk_add_f32 v[70:71], v[70:71], 1.0 op_sel_hi:[1,0]
	v_rcp_f32_e32 v68, v68
	v_rcp_f32_e32 v69, v69
	v_pk_add_f32 v[64:65], v[64:65], 1.0 op_sel_hi:[1,0]
	v_pk_add_f32 v[66:67], v[66:67], 1.0 op_sel_hi:[1,0]
	v_rcp_f32_e32 v70, v70
	v_rcp_f32_e32 v71, v71
	v_rcp_f32_e32 v64, v64
	v_rcp_f32_e32 v65, v65
	v_rcp_f32_e32 v66, v66
	v_rcp_f32_e32 v67, v67
	v_pk_fma_f32 v[52:53], v[52:53], v[72:73], v[128:129] op_sel_hi:[1,0,1]
	v_pk_fma_f32 v[54:55], v[54:55], v[72:73], v[130:131] op_sel_hi:[1,0,1]
	v_pk_mul_f32 v[56:57], v[56:57], v[68:69]
	v_pk_mul_f32 v[54:55], v[62:63], v[54:55]
	v_pk_mul_f32 v[52:53], v[60:61], v[52:53]
	v_pk_mul_f32 v[58:59], v[58:59], v[70:71]
	v_pk_mul_f32 v[60:61], v[52:53], v[64:65]
	v_pk_mul_f32 v[62:63], v[54:55], v[66:67]
	v_cvt_pk_bf16_f32 v52, v56, v57
	v_cvt_pk_bf16_f32 v53, v58, v59
	v_cvt_pk_bf16_f32 v54, v60, v61
	v_add_u32_e32 v57, 0x80, v166
	v_cvt_pk_bf16_f32 v55, v62, v63
	ds_read_b32 v56, v163 offset:320
	v_mad_i64_i32 v[58:59], s[22:23], v57, s34, v[116:117]
	v_lshl_add_u64 v[58:59], v[58:59], 0, v[118:119]
	global_store_dwordx4 v[58:59], v[52:55], off
	s_waitcnt lgkmcnt(0)
; __device__ __forceinline__ unsigned cvt_pk_bf16(float lo, float hi) { unsigned r; asm volatile("v_cvt_pk_bf16_f32 %0, %1, %2" : "=v"(r) : "v"(lo), "v"(hi)); return r; }
; #define PG8_WAIT_V(n) asm volatile("s_waitcnt vmcnt(" #n ")" ::: "memory")
; #define PG8_BAR __builtin_amdgcn_s_barrier()
;     __device__ __forceinline__ void operator()(const f32x4 (&acc)[2][2][4][2], const Unit& u, int wr, int wc, int fr, int fq, PG8_LAS unsigned char* sl) const {
;     ...
;             for (int m = 0; m < 4; ++m) { const int row = row0 + ai * HALF + m * 16; bf16_t* rowp = O + (size_t)row * ldc + col0;
;                 const float rs = __builtin_amdgcn_rsqf(sf[ai * 64 + m * 16 + fr] * (1.0f / 2048.0f) + 1e-6f);
;                 const f32x4 a0 = acc[ai][0][m][0] * rs + bw[0][0], a1 = acc[ai][0][m][1] * rs + bw[0][1], b0 = acc[ai][1][m][0] * rs + bw[1][0], b1 = acc[ai][1][m][1] * rs + bw[1][1];
;                 const f32x2 s0 = silu_mul_pk((f32x2){a0[0], a0[1]}, (f32x2){b0[0], b0[1]}), s1 = silu_mul_pk((f32x2){a0[2], a0[3]}, (f32x2){b0[2], b0[3]});
;                 const f32x2 s2 = silu_mul_pk((f32x2){a1[0], a1[1]}, (f32x2){b1[0], b1[1]}), s3 = silu_mul_pk((f32x2){a1[2], a1[3]}, (f32x2){b1[2], b1[3]});
;                 u32x4 w; w.x = cvt_pk_bf16(s0.x, s0.y); w.y = cvt_pk_bf16(s1.x, s1.y); w.z = cvt_pk_bf16(s2.x, s2.y); w.w = cvt_pk_bf16(s3.x, s3.y);
;                 *(u32x4*)rowp = w; }
; template <class Epi, class Sched, bool ALIGN_EPI = false, bool SP2 = false>
; __device__ __forceinline__ void gemm_phase(PG8_LAS unsigned char* lds, const Gemm g, const Sched& S, const Epi& E, const int tid) {
;     ...
;         cur = nxt; cA = nA; cB = nB; ++ui;
;         if constexpr (ALIGN_EPI) { if (wr == 1) PG8_BAR; }
;     }
;     PG8_WAIT_V(0);
;     if constexpr (!ALIGN_EPI) { if (wr == 0) PG8_BAR; }
;     PG8_BAR;
	v_fmamk_f32 v56, v56, 0x3a000000, v233
	v_rsq_f32_e32 v56, v56
	s_nop 0
	v_pk_fma_f32 v[48:49], v[48:49], v[56:57], v[144:145] op_sel_hi:[1,0,1]
	v_pk_fma_f32 v[50:51], v[50:51], v[56:57], v[146:147] op_sel_hi:[1,0,1]
	v_pk_fma_f32 v[46:47], v[46:47], v[56:57], v[142:143] op_sel_hi:[1,0,1]
	v_pk_fma_f32 v[44:45], v[44:45], v[56:57], v[140:141] op_sel_hi:[1,0,1]
	v_pk_fma_f32 v[40:41], v[40:41], v[56:57], v[132:133] op_sel_hi:[1,0,1]
	v_pk_fma_f32 v[42:43], v[42:43], v[56:57], v[134:135] op_sel_hi:[1,0,1]
	v_pk_mul_f32 v[52:53], v[48:49], s[72:73] op_sel_hi:[1,0]
	v_pk_mul_f32 v[54:55], v[50:51], s[72:73] op_sel_hi:[1,0]
	v_exp_f32_e32 v52, v52
	v_exp_f32_e32 v53, v53
	v_pk_mul_f32 v[42:43], v[50:51], v[42:43]
	v_pk_mul_f32 v[40:41], v[48:49], v[40:41]
	v_pk_mul_f32 v[48:49], v[44:45], s[72:73] op_sel_hi:[1,0]
	v_pk_mul_f32 v[50:51], v[46:47], s[72:73] op_sel_hi:[1,0]
	v_exp_f32_e32 v54, v54
	v_exp_f32_e32 v55, v55
	v_exp_f32_e32 v48, v48
	v_exp_f32_e32 v49, v49
	v_exp_f32_e32 v50, v50
	v_exp_f32_e32 v51, v51
	v_pk_add_f32 v[52:53], v[52:53], 1.0 op_sel_hi:[1,0]
	v_pk_add_f32 v[54:55], v[54:55], 1.0 op_sel_hi:[1,0]
	v_rcp_f32_e32 v52, v52
	v_rcp_f32_e32 v53, v53
	v_pk_add_f32 v[48:49], v[48:49], 1.0 op_sel_hi:[1,0]
	v_pk_add_f32 v[50:51], v[50:51], 1.0 op_sel_hi:[1,0]
	v_rcp_f32_e32 v54, v54
	v_rcp_f32_e32 v55, v55
	v_rcp_f32_e32 v48, v48
	v_rcp_f32_e32 v49, v49
	v_rcp_f32_e32 v50, v50
	v_rcp_f32_e32 v51, v51
	v_pk_fma_f32 v[36:37], v[36:37], v[56:57], v[128:129] op_sel_hi:[1,0,1]
	v_pk_fma_f32 v[38:39], v[38:39], v[56:57], v[130:131] op_sel_hi:[1,0,1]
	v_pk_mul_f32 v[40:41], v[40:41], v[52:53]
	v_pk_mul_f32 v[38:39], v[46:47], v[38:39]
	v_pk_mul_f32 v[36:37], v[44:45], v[36:37]
	v_pk_mul_f32 v[42:43], v[42:43], v[54:55]
	v_pk_mul_f32 v[44:45], v[36:37], v[48:49]
	v_pk_mul_f32 v[46:47], v[38:39], v[50:51]
	v_cvt_pk_bf16_f32 v36, v40, v41
	v_cvt_pk_bf16_f32 v37, v42, v43
	v_cvt_pk_bf16_f32 v38, v44, v45
	v_add_u32_e32 v41, 0x90, v166
	v_cvt_pk_bf16_f32 v39, v46, v47
	ds_read_b32 v40, v163 offset:384
	v_mad_i64_i32 v[42:43], s[22:23], v41, s34, v[116:117]
	v_lshl_add_u64 v[42:43], v[42:43], 0, v[118:119]
	global_store_dwordx4 v[42:43], v[36:39], off
	s_waitcnt lgkmcnt(0)
	v_fmamk_f32 v40, v40, 0x3a000000, v233
	v_rsq_f32_e32 v40, v40
	v_add_u32_e32 v44, 0xa0, v166
	v_add_u32_e32 v45, 0xb0, v166
	v_pk_fma_f32 v[34:35], v[34:35], v[40:41], v[146:147] op_sel_hi:[1,0,1]
	v_pk_fma_f32 v[32:33], v[32:33], v[40:41], v[144:145] op_sel_hi:[1,0,1]
	v_pk_fma_f32 v[30:31], v[30:31], v[40:41], v[142:143] op_sel_hi:[1,0,1]
	v_pk_fma_f32 v[28:29], v[28:29], v[40:41], v[140:141] op_sel_hi:[1,0,1]
	v_pk_fma_f32 v[24:25], v[24:25], v[40:41], v[132:133] op_sel_hi:[1,0,1]
	v_pk_fma_f32 v[26:27], v[26:27], v[40:41], v[134:135] op_sel_hi:[1,0,1]
	v_pk_mul_f32 v[38:39], v[34:35], s[72:73] op_sel_hi:[1,0]
	v_pk_mul_f32 v[36:37], v[32:33], s[72:73] op_sel_hi:[1,0]
	v_exp_f32_e32 v38, v38
	v_exp_f32_e32 v39, v39
	v_pk_mul_f32 v[26:27], v[34:35], v[26:27]
	v_pk_mul_f32 v[24:25], v[32:33], v[24:25]
	v_pk_mul_f32 v[32:33], v[28:29], s[72:73] op_sel_hi:[1,0]
	v_pk_mul_f32 v[34:35], v[30:31], s[72:73] op_sel_hi:[1,0]
	v_exp_f32_e32 v36, v36
	v_exp_f32_e32 v37, v37
	v_exp_f32_e32 v32, v32
	v_exp_f32_e32 v33, v33
	v_exp_f32_e32 v34, v34
	v_exp_f32_e32 v35, v35
	v_pk_add_f32 v[38:39], v[38:39], 1.0 op_sel_hi:[1,0]
	v_pk_add_f32 v[36:37], v[36:37], 1.0 op_sel_hi:[1,0]
	v_rcp_f32_e32 v38, v38
	v_rcp_f32_e32 v39, v39
	v_pk_add_f32 v[32:33], v[32:33], 1.0 op_sel_hi:[1,0]
	v_pk_add_f32 v[34:35], v[34:35], 1.0 op_sel_hi:[1,0]
	v_rcp_f32_e32 v36, v36
	v_rcp_f32_e32 v37, v37
	v_rcp_f32_e32 v32, v32
	v_rcp_f32_e32 v33, v33
	v_rcp_f32_e32 v34, v34
	v_rcp_f32_e32 v35, v35
	v_pk_fma_f32 v[20:21], v[20:21], v[40:41], v[128:129] op_sel_hi:[1,0,1]
	v_pk_fma_f32 v[22:23], v[22:23], v[40:41], v[130:131] op_sel_hi:[1,0,1]
	v_pk_mul_f32 v[26:27], v[26:27], v[38:39]
	v_pk_mul_f32 v[22:23], v[30:31], v[22:23]
	v_pk_mul_f32 v[20:21], v[28:29], v[20:21]
	v_pk_mul_f32 v[24:25], v[24:25], v[36:37]
	v_pk_mul_f32 v[28:29], v[20:21], v[32:33]
	v_pk_mul_f32 v[30:31], v[22:23], v[34:35]
	v_cvt_pk_bf16_f32 v20, v24, v25
	v_cvt_pk_bf16_f32 v21, v26, v27
	v_cvt_pk_bf16_f32 v22, v28, v29
	v_mad_i64_i32 v[24:25], s[22:23], v44, s34, v[116:117]
	v_cvt_pk_bf16_f32 v23, v30, v31
	ds_read_b32 v26, v163 offset:448
	v_lshl_add_u64 v[24:25], v[24:25], 0, v[118:119]
	global_store_dwordx4 v[24:25], v[20:23], off
	s_waitcnt lgkmcnt(0)
	s_nop 0
	v_fmamk_f32 v20, v26, 0x3a000000, v233
	v_rsq_f32_e32 v20, v20
	v_mad_i64_i32 v[22:23], s[22:23], v45, s34, v[116:117]
	v_lshl_add_u64 v[22:23], v[22:23], 0, v[118:119]
	v_pk_fma_f32 v[18:19], v[18:19], v[20:21], v[146:147] op_sel_hi:[1,0,1]
	v_pk_fma_f32 v[16:17], v[16:17], v[20:21], v[144:145] op_sel_hi:[1,0,1]
	v_pk_fma_f32 v[14:15], v[14:15], v[20:21], v[142:143] op_sel_hi:[1,0,1]
	v_pk_fma_f32 v[12:13], v[12:13], v[20:21], v[140:141] op_sel_hi:[1,0,1]
	v_pk_fma_f32 v[8:9], v[8:9], v[20:21], v[132:133] op_sel_hi:[1,0,1]
	v_pk_fma_f32 v[10:11], v[10:11], v[20:21], v[134:135] op_sel_hi:[1,0,1]
	v_pk_fma_f32 v[4:5], v[4:5], v[20:21], v[128:129] op_sel_hi:[1,0,1]
	v_pk_fma_f32 v[6:7], v[6:7], v[20:21], v[130:131] op_sel_hi:[1,0,1]
	v_pk_mul_f32 v[20:21], v[16:17], s[72:73] op_sel_hi:[1,0]
	v_pk_mul_f32 v[24:25], v[18:19], s[72:73] op_sel_hi:[1,0]
	v_pk_mul_f32 v[10:11], v[18:19], v[10:11]
	v_pk_mul_f32 v[8:9], v[16:17], v[8:9]
	v_pk_mul_f32 v[16:17], v[12:13], s[72:73] op_sel_hi:[1,0]
	v_pk_mul_f32 v[18:19], v[14:15], s[72:73] op_sel_hi:[1,0]
	v_exp_f32_e32 v20, v20
	v_exp_f32_e32 v21, v21
	v_exp_f32_e32 v24, v24
	v_exp_f32_e32 v25, v25
	v_exp_f32_e32 v16, v16
	v_exp_f32_e32 v17, v17
	v_exp_f32_e32 v18, v18
	v_exp_f32_e32 v19, v19
	v_pk_add_f32 v[20:21], v[20:21], 1.0 op_sel_hi:[1,0]
	v_pk_add_f32 v[24:25], v[24:25], 1.0 op_sel_hi:[1,0]
	v_pk_add_f32 v[16:17], v[16:17], 1.0 op_sel_hi:[1,0]
	v_pk_add_f32 v[18:19], v[18:19], 1.0 op_sel_hi:[1,0]
	v_rcp_f32_e32 v20, v20
	v_rcp_f32_e32 v21, v21
	v_rcp_f32_e32 v24, v24
	v_rcp_f32_e32 v25, v25
	v_rcp_f32_e32 v16, v16
	v_rcp_f32_e32 v17, v17
	v_rcp_f32_e32 v18, v18
	v_rcp_f32_e32 v19, v19
	v_pk_mul_f32 v[6:7], v[14:15], v[6:7]
	v_pk_mul_f32 v[4:5], v[12:13], v[4:5]
	v_pk_mul_f32 v[8:9], v[8:9], v[20:21]
	v_pk_mul_f32 v[10:11], v[10:11], v[24:25]
	v_pk_mul_f32 v[12:13], v[4:5], v[16:17]
	v_pk_mul_f32 v[14:15], v[6:7], v[18:19]
	v_cvt_pk_bf16_f32 v4, v8, v9
	v_cvt_pk_bf16_f32 v5, v10, v11
	v_cvt_pk_bf16_f32 v6, v12, v13
	s_nop 0
	v_cvt_pk_bf16_f32 v7, v14, v15
	global_store_dwordx4 v[22:23], v[4:7], off
	s_cbranch_vccnz .LBB0_262
	s_andn2_b64 vcc, exec, s[10:11]
	s_cbranch_vccnz .LBB0_261
	s_nop 0
	s_branch .LBB0_261
.LBB0_274:
	s_waitcnt vmcnt(0)
	s_and_b64 vcc, exec, s[12:13]
	s_cbranch_vccz .Lup_na_skip
	s_barrier
.Lup_na_skip:
	v_readlane_b32 s28, v255, 9
	s_barrier
	v_readlane_b32 s29, v255, 10
